# speedup vs baseline: 1.0229x; 1.0004x over previous
.LBB0_169:
	v_max_u32_dpp v103, v99, v99 quad_perm:[1,0,3,2] row_mask:0xf bank_mask:0xf
	s_nop 1
	v_max_u32_dpp v103, v103, v103 quad_perm:[2,3,0,1] row_mask:0xf bank_mask:0xf
	s_nop 1
	v_max_u32_dpp v103, v103, v103 row_half_mirror row_mask:0xf bank_mask:0xf
	s_nop 1
	v_max_u32_dpp v103, v103, v103 row_mirror row_mask:0xf bank_mask:0xf
	v_cmp_eq_u32_e32 vcc, v99, v103
	s_nop 1
	v_cndmask_b32_e32 v99, v99, v101, vcc
	v_cndmask_b32_e32 v101, v101, v102, vcc
	v_cndmask_b32_e32 v102, v102, v100, vcc
	v_cndmask_b32_e64 v100, v100, 0, vcc
	v_cmp_eq_u32_e32 vcc, s0, v83
	s_add_i32 s0, s0, 1
	s_cmp_lg_u32 s0, 16
	v_cndmask_b32_e32 v98, v98, v103, vcc
	s_cbranch_scc1 .LBB0_169
	v_not_b32_e32 v99, v98
	v_lshrrev_b32_e32 v99, 4, v99
	v_and_or_b32 v99, v99, 15, v156
	v_lshlrev_b32_e32 v99, 2, v99
	v_cmp_lt_i32_e32 vcc, -1, v98
	ds_bpermute_b32 v96, v99, v96
	s_movk_i32 s0, 0xff00
	v_cndmask_b32_e64 v99, v189, -1, vcc
	v_bitop3_b32 v99, v99, v98, s0 bitop3:0x78
	ds_bpermute_b32 v100, v157, v99
	v_bitop3_b32 v98, v98, v156, 15 bitop3:0xce
	v_lshlrev_b32_e32 v98, 2, v98
	ds_bpermute_b32 v97, v98, v97
	s_waitcnt lgkmcnt(2)
	v_lshlrev_b32_e32 v96, 7, v96
	s_waitcnt lgkmcnt(1)
	v_sub_f32_e32 v98, v99, v100
	v_mul_f32_e32 v98, 0x3fb8aa3b, v98
	v_exp_f32_e32 v112, v98
	v_and_b32_e32 v96, 0x3f80, v96
	s_waitcnt lgkmcnt(0)
	v_and_b32_e32 v97, 0x7f, v97
	v_bitop3_b32 v113, v97, s74, v96 bitop3:0x36
	v_add_f32_dpp v96, v112, v112 quad_perm:[1,0,3,2] row_mask:0xf bank_mask:0xf bound_ctrl:1
	v_readlane_b32 s0, v254, 52
	s_waitcnt vmcnt(18)
	v_lshlrev_b32_e32 v120, 16, v46
	v_add_f32_dpp v96, v96, v96 quad_perm:[2,3,0,1] row_mask:0xf bank_mask:0xf bound_ctrl:1
	v_add_u32_e32 v226, s0, v94
	v_and_b32_e32 v121, 0xffff0000, v46
	v_add_f32_dpp v96, v96, v96 row_half_mirror row_mask:0xf bank_mask:0xf bound_ctrl:1
	v_lshlrev_b32_e32 v46, 16, v47
	v_and_b32_e32 v47, 0xffff0000, v47
	v_add_f32_dpp v114, v96, v96 row_mirror row_mask:0xf bank_mask:0xf bound_ctrl:1
	v_min_i32_e32 v96, 0x3fff, v226
	v_ashrrev_i32_e32 v97, 31, v96
	v_lshlrev_b64 v[96:97], 12, v[96:97]
	v_lshl_add_u64 v[96:97], v[92:93], 0, v[96:97]
	global_load_dwordx2 v[110:111], v[96:97], off
	global_load_dwordx2 v[108:109], v[96:97], off offset:512
	global_load_dwordx2 v[106:107], v[96:97], off offset:1024
	global_load_dwordx2 v[104:105], v[96:97], off offset:1536
	global_load_dwordx2 v[102:103], v[96:97], off offset:2048
	global_load_dwordx2 v[100:101], v[96:97], off offset:2560
	global_load_dwordx2 v[98:99], v[96:97], off offset:3072
	s_nop 0
	global_load_dwordx2 v[96:97], v[96:97], off offset:3584
	v_div_scale_f32 v115, s[6:7], v114, v114, v112
	v_rcp_f32_e32 v116, v115
	v_lshlrev_b32_e32 v122, 16, v48
	v_and_b32_e32 v123, 0xffff0000, v48
	v_lshlrev_b32_e32 v48, 16, v49
	v_fma_f32 v117, -v115, v116, 1.0
	v_fmac_f32_e32 v116, v117, v116
	v_div_scale_f32 v117, vcc, v112, v114, v112
	v_mul_f32_e32 v118, v117, v116
	v_fma_f32 v119, -v115, v118, v117
	v_fmac_f32_e32 v118, v119, v116
	v_fma_f32 v115, -v115, v118, v117
	v_div_fmas_f32 v115, v115, v116, v118
	v_div_fixup_f32 v112, v115, v114, v112
	ds_write2st64_b32 v154, v112, v113 offset0:137 offset1:139
	s_waitcnt vmcnt(24)
	v_lshlrev_b32_e32 v112, 16, v54
	v_and_b32_e32 v113, 0xffff0000, v54
	v_lshlrev_b32_e32 v54, 16, v55
	v_and_b32_e32 v55, 0xffff0000, v55
	v_lshlrev_b32_e32 v114, 16, v56
	v_and_b32_e32 v115, 0xffff0000, v56
	v_lshlrev_b32_e32 v56, 16, v57
	v_and_b32_e32 v57, 0xffff0000, v57
	v_lshlrev_b32_e32 v116, 16, v50
	v_and_b32_e32 v117, 0xffff0000, v50
	v_lshlrev_b32_e32 v50, 16, v51
	v_and_b32_e32 v51, 0xffff0000, v51
	v_lshlrev_b32_e32 v118, 16, v52
	v_and_b32_e32 v119, 0xffff0000, v52
	v_lshlrev_b32_e32 v52, 16, v53
	v_and_b32_e32 v53, 0xffff0000, v53
	v_and_b32_e32 v49, 0xffff0000, v49
	v_lshlrev_b32_e32 v126, 16, v38
	v_and_b32_e32 v127, 0xffff0000, v38
	v_lshlrev_b32_e32 v38, 16, v39
	v_and_b32_e32 v39, 0xffff0000, v39
	v_lshlrev_b32_e32 v128, 16, v40
	v_and_b32_e32 v129, 0xffff0000, v40
	v_lshlrev_b32_e32 v40, 16, v41
	v_and_b32_e32 v41, 0xffff0000, v41
	s_waitcnt vmcnt(20)
	v_lshlrev_b32_e32 v130, 16, v42
	v_and_b32_e32 v131, 0xffff0000, v42
	v_lshlrev_b32_e32 v42, 16, v43
	v_and_b32_e32 v43, 0xffff0000, v43
	v_lshlrev_b32_e32 v132, 16, v44
	v_and_b32_e32 v133, 0xffff0000, v44
	v_lshlrev_b32_e32 v44, 16, v45
	v_and_b32_e32 v45, 0xffff0000, v45
	v_lshlrev_b32_e32 v134, 16, v34
	v_and_b32_e32 v135, 0xffff0000, v34
	v_lshlrev_b32_e32 v34, 16, v35
	v_and_b32_e32 v35, 0xffff0000, v35
	v_lshlrev_b32_e32 v136, 16, v36
	v_and_b32_e32 v137, 0xffff0000, v36
	v_lshlrev_b32_e32 v36, 16, v37
	v_and_b32_e32 v37, 0xffff0000, v37
	v_lshlrev_b32_e32 v138, 16, v30
	v_and_b32_e32 v139, 0xffff0000, v30
	v_lshlrev_b32_e32 v140, 16, v31
	v_and_b32_e32 v141, 0xffff0000, v31
	v_lshlrev_b32_e32 v142, 16, v32
	v_and_b32_e32 v143, 0xffff0000, v32
	v_lshlrev_b32_e32 v144, 16, v33
	v_and_b32_e32 v145, 0xffff0000, v33
	v_lshlrev_b32_e32 v146, 16, v26
	v_and_b32_e32 v147, 0xffff0000, v26
	v_lshlrev_b32_e32 v148, 16, v27
	v_and_b32_e32 v149, 0xffff0000, v27
	v_lshlrev_b32_e32 v150, 16, v28
	v_and_b32_e32 v151, 0xffff0000, v28
	v_lshlrev_b32_e32 v152, 16, v29
	v_and_b32_e32 v153, 0xffff0000, v29
	ds_read_b32 v240, v217 offset:35376
	v_lshlrev_b32_e32 v245, 2, v124
	v_add_u32_e32 v245, 0xb800, v245
	v_add_u32_e32 v227, 0x8a00, v217
	s_movk_i32 s0, 0x200
	s_mov_b32 s2, 0
	v_cndmask_b32_e64 v244, v245, v221, s[44:45]
	s_waitcnt lgkmcnt(0)
	ds_read_b32 v241, v227 offset:64
	s_waitcnt vmcnt(5)
	v_mad_u64_u32 v[242:243], s[6:7], v240, s0, v[84:85]
	global_load_dwordx4 v[30:33], v[242:243], off
	global_load_dwordx4 v[26:29], v[242:243], off offset:256
	v_cvt_scalef32_pk_f32_fp4 v[196:197], v66, 1.0
	v_cvt_scalef32_pk_f32_fp4 v[198:199], v66, 1.0 op_sel:[1,0,0]
	v_cvt_scalef32_pk_f32_fp4 v[230:231], v66, 1.0 op_sel:[0,1,0]
	v_cvt_scalef32_pk_f32_fp4 v[232:233], v66, 1.0 op_sel:[1,1,0]
	v_pk_fma_f32 v[234:235], v[112:113], v[196:197], 0 op_sel_hi:[1,1,0]
	v_pk_fma_f32 v[236:237], v[54:55], v[198:199], 0 op_sel_hi:[1,1,0]
	v_pk_fma_f32 v[234:235], v[114:115], v[230:231], v[234:235]
	v_pk_fma_f32 v[236:237], v[56:57], v[232:233], v[236:237]
	v_cvt_scalef32_pk_f32_fp4 v[196:197], v67, 1.0
	v_cvt_scalef32_pk_f32_fp4 v[198:199], v67, 1.0 op_sel:[1,0,0]
	v_cvt_scalef32_pk_f32_fp4 v[230:231], v67, 1.0 op_sel:[0,1,0]
	v_cvt_scalef32_pk_f32_fp4 v[232:233], v67, 1.0 op_sel:[1,1,0]
	v_pk_fma_f32 v[234:235], v[116:117], v[196:197], v[234:235]
	v_pk_fma_f32 v[236:237], v[50:51], v[198:199], v[236:237]
	v_pk_fma_f32 v[234:235], v[118:119], v[230:231], v[234:235]
	v_pk_fma_f32 v[236:237], v[52:53], v[232:233], v[236:237]
	v_cvt_scalef32_pk_f32_fp4 v[196:197], v68, 1.0
	v_cvt_scalef32_pk_f32_fp4 v[198:199], v68, 1.0 op_sel:[1,0,0]
	v_cvt_scalef32_pk_f32_fp4 v[230:231], v68, 1.0 op_sel:[0,1,0]
	v_cvt_scalef32_pk_f32_fp4 v[232:233], v68, 1.0 op_sel:[1,1,0]
	v_pk_fma_f32 v[234:235], v[120:121], v[196:197], v[234:235]
	v_pk_fma_f32 v[236:237], v[46:47], v[198:199], v[236:237]
	v_pk_fma_f32 v[234:235], v[122:123], v[230:231], v[234:235]
	v_pk_fma_f32 v[236:237], v[48:49], v[232:233], v[236:237]
	v_cvt_scalef32_pk_f32_fp4 v[196:197], v69, 1.0
	v_cvt_scalef32_pk_f32_fp4 v[198:199], v69, 1.0 op_sel:[1,0,0]
	v_cvt_scalef32_pk_f32_fp4 v[230:231], v69, 1.0 op_sel:[0,1,0]
	v_cvt_scalef32_pk_f32_fp4 v[232:233], v69, 1.0 op_sel:[1,1,0]
	v_pk_fma_f32 v[234:235], v[126:127], v[196:197], v[234:235]
	v_pk_fma_f32 v[236:237], v[38:39], v[198:199], v[236:237]
	v_pk_fma_f32 v[234:235], v[128:129], v[230:231], v[234:235]
	v_pk_fma_f32 v[236:237], v[40:41], v[232:233], v[236:237]
	s_waitcnt vmcnt(6)
	v_cvt_scalef32_pk_f32_fp4 v[196:197], v58, 1.0
	v_cvt_scalef32_pk_f32_fp4 v[198:199], v58, 1.0 op_sel:[1,0,0]
	v_cvt_scalef32_pk_f32_fp4 v[230:231], v58, 1.0 op_sel:[0,1,0]
	v_cvt_scalef32_pk_f32_fp4 v[232:233], v58, 1.0 op_sel:[1,1,0]
	v_pk_fma_f32 v[234:235], v[130:131], v[196:197], v[234:235]
	v_pk_fma_f32 v[236:237], v[42:43], v[198:199], v[236:237]
	v_pk_fma_f32 v[234:235], v[132:133], v[230:231], v[234:235]
	v_pk_fma_f32 v[236:237], v[44:45], v[232:233], v[236:237]
	v_cvt_scalef32_pk_f32_fp4 v[196:197], v59, 1.0
	v_cvt_scalef32_pk_f32_fp4 v[198:199], v59, 1.0 op_sel:[1,0,0]
	v_cvt_scalef32_pk_f32_fp4 v[230:231], v59, 1.0 op_sel:[0,1,0]
	v_cvt_scalef32_pk_f32_fp4 v[232:233], v59, 1.0 op_sel:[1,1,0]
	v_pk_fma_f32 v[234:235], v[134:135], v[196:197], v[234:235]
	v_pk_fma_f32 v[236:237], v[34:35], v[198:199], v[236:237]
	v_pk_fma_f32 v[234:235], v[136:137], v[230:231], v[234:235]
	v_pk_fma_f32 v[236:237], v[36:37], v[232:233], v[236:237]
	v_cvt_scalef32_pk_f32_fp4 v[196:197], v60, 1.0
	v_cvt_scalef32_pk_f32_fp4 v[198:199], v60, 1.0 op_sel:[1,0,0]
	v_cvt_scalef32_pk_f32_fp4 v[230:231], v60, 1.0 op_sel:[0,1,0]
	v_cvt_scalef32_pk_f32_fp4 v[232:233], v60, 1.0 op_sel:[1,1,0]
	v_pk_fma_f32 v[234:235], v[138:139], v[196:197], v[234:235]
	v_pk_fma_f32 v[236:237], v[140:141], v[198:199], v[236:237]
	v_pk_fma_f32 v[234:235], v[142:143], v[230:231], v[234:235]
	v_pk_fma_f32 v[236:237], v[144:145], v[232:233], v[236:237]
	v_cvt_scalef32_pk_f32_fp4 v[196:197], v61, 1.0
	v_cvt_scalef32_pk_f32_fp4 v[198:199], v61, 1.0 op_sel:[1,0,0]
	v_cvt_scalef32_pk_f32_fp4 v[230:231], v61, 1.0 op_sel:[0,1,0]
	v_cvt_scalef32_pk_f32_fp4 v[232:233], v61, 1.0 op_sel:[1,1,0]
	v_pk_fma_f32 v[234:235], v[146:147], v[196:197], v[234:235]
	v_pk_fma_f32 v[236:237], v[148:149], v[198:199], v[236:237]
	v_pk_fma_f32 v[234:235], v[150:151], v[230:231], v[234:235]
	v_pk_fma_f32 v[236:237], v[152:153], v[232:233], v[236:237]
	v_add_f32_e32 v238, v236, v237
	v_add_f32_e32 v242, v234, v235
	v_add_f32_e32 v238, v242, v238
	s_waitcnt lgkmcnt(0)
	s_nop 0
	v_add_f32_dpp v238, v238, v238 quad_perm:[1,0,3,2] row_mask:0xf bank_mask:0xf bound_ctrl:1
	ds_read_b32 v240, v227 offset:80
	s_waitcnt vmcnt(5)
	v_add_f32_dpp v238, v238, v238 quad_perm:[2,3,0,1] row_mask:0xf bank_mask:0xf bound_ctrl:1
	v_mad_u64_u32 v[242:243], s[6:7], v241, s0, v[84:85]
	global_load_dwordx4 v[66:69], v[242:243], off
	v_add_f32_dpp v238, v238, v238 row_half_mirror row_mask:0xf bank_mask:0xf bound_ctrl:1
	global_load_dwordx4 v[58:61], v[242:243], off offset:256
	s_nop 0
	v_add_f32_dpp v238, v238, v238 row_mirror row_mask:0xf bank_mask:0xf bound_ctrl:1
	ds_write_b32 v244, v238 offset:0
.Lpu_loop:
	v_cvt_scalef32_pk_f32_fp4 v[196:197], v74, 1.0
	v_cvt_scalef32_pk_f32_fp4 v[198:199], v74, 1.0 op_sel:[1,0,0]
	v_cvt_scalef32_pk_f32_fp4 v[230:231], v74, 1.0 op_sel:[0,1,0]
	v_cvt_scalef32_pk_f32_fp4 v[232:233], v74, 1.0 op_sel:[1,1,0]
	v_pk_fma_f32 v[234:235], v[112:113], v[196:197], 0 op_sel_hi:[1,1,0]
	v_pk_fma_f32 v[236:237], v[54:55], v[198:199], 0 op_sel_hi:[1,1,0]
	v_pk_fma_f32 v[234:235], v[114:115], v[230:231], v[234:235]
	v_pk_fma_f32 v[236:237], v[56:57], v[232:233], v[236:237]
	v_cvt_scalef32_pk_f32_fp4 v[196:197], v75, 1.0
	v_cvt_scalef32_pk_f32_fp4 v[198:199], v75, 1.0 op_sel:[1,0,0]
	v_cvt_scalef32_pk_f32_fp4 v[230:231], v75, 1.0 op_sel:[0,1,0]
	v_cvt_scalef32_pk_f32_fp4 v[232:233], v75, 1.0 op_sel:[1,1,0]
	v_pk_fma_f32 v[234:235], v[116:117], v[196:197], v[234:235]
	v_pk_fma_f32 v[236:237], v[50:51], v[198:199], v[236:237]
	v_pk_fma_f32 v[234:235], v[118:119], v[230:231], v[234:235]
	v_pk_fma_f32 v[236:237], v[52:53], v[232:233], v[236:237]
	v_cvt_scalef32_pk_f32_fp4 v[196:197], v76, 1.0
	v_cvt_scalef32_pk_f32_fp4 v[198:199], v76, 1.0 op_sel:[1,0,0]
	v_cvt_scalef32_pk_f32_fp4 v[230:231], v76, 1.0 op_sel:[0,1,0]
	v_cvt_scalef32_pk_f32_fp4 v[232:233], v76, 1.0 op_sel:[1,1,0]
	v_pk_fma_f32 v[234:235], v[120:121], v[196:197], v[234:235]
	v_pk_fma_f32 v[236:237], v[46:47], v[198:199], v[236:237]
	v_pk_fma_f32 v[234:235], v[122:123], v[230:231], v[234:235]
	v_pk_fma_f32 v[236:237], v[48:49], v[232:233], v[236:237]
	v_cvt_scalef32_pk_f32_fp4 v[196:197], v77, 1.0
	v_cvt_scalef32_pk_f32_fp4 v[198:199], v77, 1.0 op_sel:[1,0,0]
	v_cvt_scalef32_pk_f32_fp4 v[230:231], v77, 1.0 op_sel:[0,1,0]
	v_cvt_scalef32_pk_f32_fp4 v[232:233], v77, 1.0 op_sel:[1,1,0]
	v_pk_fma_f32 v[234:235], v[126:127], v[196:197], v[234:235]
	v_pk_fma_f32 v[236:237], v[38:39], v[198:199], v[236:237]
	v_pk_fma_f32 v[234:235], v[128:129], v[230:231], v[234:235]
	v_pk_fma_f32 v[236:237], v[40:41], v[232:233], v[236:237]
	s_waitcnt vmcnt(6)
	v_cvt_scalef32_pk_f32_fp4 v[196:197], v62, 1.0
	v_cvt_scalef32_pk_f32_fp4 v[198:199], v62, 1.0 op_sel:[1,0,0]
	v_cvt_scalef32_pk_f32_fp4 v[230:231], v62, 1.0 op_sel:[0,1,0]
	v_cvt_scalef32_pk_f32_fp4 v[232:233], v62, 1.0 op_sel:[1,1,0]
	v_pk_fma_f32 v[234:235], v[130:131], v[196:197], v[234:235]
	v_pk_fma_f32 v[236:237], v[42:43], v[198:199], v[236:237]
	v_pk_fma_f32 v[234:235], v[132:133], v[230:231], v[234:235]
	v_pk_fma_f32 v[236:237], v[44:45], v[232:233], v[236:237]
	v_cvt_scalef32_pk_f32_fp4 v[196:197], v63, 1.0
	v_cvt_scalef32_pk_f32_fp4 v[198:199], v63, 1.0 op_sel:[1,0,0]
	v_cvt_scalef32_pk_f32_fp4 v[230:231], v63, 1.0 op_sel:[0,1,0]
	v_cvt_scalef32_pk_f32_fp4 v[232:233], v63, 1.0 op_sel:[1,1,0]
	v_pk_fma_f32 v[234:235], v[134:135], v[196:197], v[234:235]
	v_pk_fma_f32 v[236:237], v[34:35], v[198:199], v[236:237]
	v_pk_fma_f32 v[234:235], v[136:137], v[230:231], v[234:235]
	v_pk_fma_f32 v[236:237], v[36:37], v[232:233], v[236:237]
	v_cvt_scalef32_pk_f32_fp4 v[196:197], v64, 1.0
	v_cvt_scalef32_pk_f32_fp4 v[198:199], v64, 1.0 op_sel:[1,0,0]
	v_cvt_scalef32_pk_f32_fp4 v[230:231], v64, 1.0 op_sel:[0,1,0]
	v_cvt_scalef32_pk_f32_fp4 v[232:233], v64, 1.0 op_sel:[1,1,0]
	v_pk_fma_f32 v[234:235], v[138:139], v[196:197], v[234:235]
	v_pk_fma_f32 v[236:237], v[140:141], v[198:199], v[236:237]
	v_pk_fma_f32 v[234:235], v[142:143], v[230:231], v[234:235]
	v_pk_fma_f32 v[236:237], v[144:145], v[232:233], v[236:237]
	v_cvt_scalef32_pk_f32_fp4 v[196:197], v65, 1.0
	v_cvt_scalef32_pk_f32_fp4 v[198:199], v65, 1.0 op_sel:[1,0,0]
	v_cvt_scalef32_pk_f32_fp4 v[230:231], v65, 1.0 op_sel:[0,1,0]
	v_cvt_scalef32_pk_f32_fp4 v[232:233], v65, 1.0 op_sel:[1,1,0]
	v_pk_fma_f32 v[234:235], v[146:147], v[196:197], v[234:235]
	v_pk_fma_f32 v[236:237], v[148:149], v[198:199], v[236:237]
	v_pk_fma_f32 v[234:235], v[150:151], v[230:231], v[234:235]
	v_pk_fma_f32 v[236:237], v[152:153], v[232:233], v[236:237]
	v_add_f32_e32 v239, v236, v237
	v_add_f32_e32 v242, v234, v235
	v_add_f32_e32 v239, v242, v239
	s_waitcnt lgkmcnt(0)
	s_nop 0
	v_add_f32_dpp v239, v239, v239 quad_perm:[1,0,3,2] row_mask:0xf bank_mask:0xf bound_ctrl:1
	ds_read_b32 v241, v227 offset:96
	s_waitcnt vmcnt(5)
	v_add_f32_dpp v239, v239, v239 quad_perm:[2,3,0,1] row_mask:0xf bank_mask:0xf bound_ctrl:1
	v_mad_u64_u32 v[242:243], s[6:7], v240, s0, v[84:85]
	global_load_dwordx4 v[74:77], v[242:243], off
	v_add_f32_dpp v239, v239, v239 row_half_mirror row_mask:0xf bank_mask:0xf bound_ctrl:1
	global_load_dwordx4 v[62:65], v[242:243], off offset:256
	s_nop 0
	v_add_f32_dpp v239, v239, v239 row_mirror row_mask:0xf bank_mask:0xf bound_ctrl:1
	ds_write_b32 v244, v239 offset:16
	v_cvt_scalef32_pk_f32_fp4 v[196:197], v78, 1.0
	v_cvt_scalef32_pk_f32_fp4 v[198:199], v78, 1.0 op_sel:[1,0,0]
	v_cvt_scalef32_pk_f32_fp4 v[230:231], v78, 1.0 op_sel:[0,1,0]
	v_cvt_scalef32_pk_f32_fp4 v[232:233], v78, 1.0 op_sel:[1,1,0]
	v_pk_fma_f32 v[234:235], v[112:113], v[196:197], 0 op_sel_hi:[1,1,0]
	v_pk_fma_f32 v[236:237], v[54:55], v[198:199], 0 op_sel_hi:[1,1,0]
	v_pk_fma_f32 v[234:235], v[114:115], v[230:231], v[234:235]
	v_pk_fma_f32 v[236:237], v[56:57], v[232:233], v[236:237]
	v_cvt_scalef32_pk_f32_fp4 v[196:197], v79, 1.0
	v_cvt_scalef32_pk_f32_fp4 v[198:199], v79, 1.0 op_sel:[1,0,0]
	v_cvt_scalef32_pk_f32_fp4 v[230:231], v79, 1.0 op_sel:[0,1,0]
	v_cvt_scalef32_pk_f32_fp4 v[232:233], v79, 1.0 op_sel:[1,1,0]
	v_pk_fma_f32 v[234:235], v[116:117], v[196:197], v[234:235]
	v_pk_fma_f32 v[236:237], v[50:51], v[198:199], v[236:237]
	v_pk_fma_f32 v[234:235], v[118:119], v[230:231], v[234:235]
	v_pk_fma_f32 v[236:237], v[52:53], v[232:233], v[236:237]
	v_cvt_scalef32_pk_f32_fp4 v[196:197], v80, 1.0
	v_cvt_scalef32_pk_f32_fp4 v[198:199], v80, 1.0 op_sel:[1,0,0]
	v_cvt_scalef32_pk_f32_fp4 v[230:231], v80, 1.0 op_sel:[0,1,0]
	v_cvt_scalef32_pk_f32_fp4 v[232:233], v80, 1.0 op_sel:[1,1,0]
	v_pk_fma_f32 v[234:235], v[120:121], v[196:197], v[234:235]
	v_pk_fma_f32 v[236:237], v[46:47], v[198:199], v[236:237]
	v_pk_fma_f32 v[234:235], v[122:123], v[230:231], v[234:235]
	v_pk_fma_f32 v[236:237], v[48:49], v[232:233], v[236:237]
	v_cvt_scalef32_pk_f32_fp4 v[196:197], v81, 1.0
	v_cvt_scalef32_pk_f32_fp4 v[198:199], v81, 1.0 op_sel:[1,0,0]
	v_cvt_scalef32_pk_f32_fp4 v[230:231], v81, 1.0 op_sel:[0,1,0]
	v_cvt_scalef32_pk_f32_fp4 v[232:233], v81, 1.0 op_sel:[1,1,0]
	v_pk_fma_f32 v[234:235], v[126:127], v[196:197], v[234:235]
	v_pk_fma_f32 v[236:237], v[38:39], v[198:199], v[236:237]
	v_pk_fma_f32 v[234:235], v[128:129], v[230:231], v[234:235]
	v_pk_fma_f32 v[236:237], v[40:41], v[232:233], v[236:237]
	s_waitcnt vmcnt(6)
	v_cvt_scalef32_pk_f32_fp4 v[196:197], v70, 1.0
	v_cvt_scalef32_pk_f32_fp4 v[198:199], v70, 1.0 op_sel:[1,0,0]
	v_cvt_scalef32_pk_f32_fp4 v[230:231], v70, 1.0 op_sel:[0,1,0]
	v_cvt_scalef32_pk_f32_fp4 v[232:233], v70, 1.0 op_sel:[1,1,0]
	v_pk_fma_f32 v[234:235], v[130:131], v[196:197], v[234:235]
	v_pk_fma_f32 v[236:237], v[42:43], v[198:199], v[236:237]
	v_pk_fma_f32 v[234:235], v[132:133], v[230:231], v[234:235]
	v_pk_fma_f32 v[236:237], v[44:45], v[232:233], v[236:237]
	v_cvt_scalef32_pk_f32_fp4 v[196:197], v71, 1.0
	v_cvt_scalef32_pk_f32_fp4 v[198:199], v71, 1.0 op_sel:[1,0,0]
	v_cvt_scalef32_pk_f32_fp4 v[230:231], v71, 1.0 op_sel:[0,1,0]
	v_cvt_scalef32_pk_f32_fp4 v[232:233], v71, 1.0 op_sel:[1,1,0]
	v_pk_fma_f32 v[234:235], v[134:135], v[196:197], v[234:235]
	v_pk_fma_f32 v[236:237], v[34:35], v[198:199], v[236:237]
	v_pk_fma_f32 v[234:235], v[136:137], v[230:231], v[234:235]
	v_pk_fma_f32 v[236:237], v[36:37], v[232:233], v[236:237]
	v_cvt_scalef32_pk_f32_fp4 v[196:197], v72, 1.0
	v_cvt_scalef32_pk_f32_fp4 v[198:199], v72, 1.0 op_sel:[1,0,0]
	v_cvt_scalef32_pk_f32_fp4 v[230:231], v72, 1.0 op_sel:[0,1,0]
	v_cvt_scalef32_pk_f32_fp4 v[232:233], v72, 1.0 op_sel:[1,1,0]
	v_pk_fma_f32 v[234:235], v[138:139], v[196:197], v[234:235]
	v_pk_fma_f32 v[236:237], v[140:141], v[198:199], v[236:237]
	v_pk_fma_f32 v[234:235], v[142:143], v[230:231], v[234:235]
	v_pk_fma_f32 v[236:237], v[144:145], v[232:233], v[236:237]
	v_cvt_scalef32_pk_f32_fp4 v[196:197], v73, 1.0
	v_cvt_scalef32_pk_f32_fp4 v[198:199], v73, 1.0 op_sel:[1,0,0]
	v_cvt_scalef32_pk_f32_fp4 v[230:231], v73, 1.0 op_sel:[0,1,0]
	v_cvt_scalef32_pk_f32_fp4 v[232:233], v73, 1.0 op_sel:[1,1,0]
	v_pk_fma_f32 v[234:235], v[146:147], v[196:197], v[234:235]
	v_pk_fma_f32 v[236:237], v[148:149], v[198:199], v[236:237]
	v_pk_fma_f32 v[234:235], v[150:151], v[230:231], v[234:235]
	v_pk_fma_f32 v[236:237], v[152:153], v[232:233], v[236:237]
	v_add_f32_e32 v238, v236, v237
	v_add_f32_e32 v242, v234, v235
	v_add_f32_e32 v238, v242, v238
	s_waitcnt lgkmcnt(0)
	s_nop 0
	v_add_f32_dpp v238, v238, v238 quad_perm:[1,0,3,2] row_mask:0xf bank_mask:0xf bound_ctrl:1
	ds_read_b32 v240, v227 offset:112
	s_waitcnt vmcnt(5)
	v_add_f32_dpp v238, v238, v238 quad_perm:[2,3,0,1] row_mask:0xf bank_mask:0xf bound_ctrl:1
	v_mad_u64_u32 v[242:243], s[6:7], v241, s0, v[84:85]
	global_load_dwordx4 v[78:81], v[242:243], off
	v_add_f32_dpp v238, v238, v238 row_half_mirror row_mask:0xf bank_mask:0xf bound_ctrl:1
	global_load_dwordx4 v[70:73], v[242:243], off offset:256
	s_nop 0
	v_add_f32_dpp v238, v238, v238 row_mirror row_mask:0xf bank_mask:0xf bound_ctrl:1
	ds_write_b32 v244, v238 offset:32
	v_cvt_scalef32_pk_f32_fp4 v[196:197], v30, 1.0
	v_cvt_scalef32_pk_f32_fp4 v[198:199], v30, 1.0 op_sel:[1,0,0]
	v_cvt_scalef32_pk_f32_fp4 v[230:231], v30, 1.0 op_sel:[0,1,0]
	v_cvt_scalef32_pk_f32_fp4 v[232:233], v30, 1.0 op_sel:[1,1,0]
	v_pk_fma_f32 v[234:235], v[112:113], v[196:197], 0 op_sel_hi:[1,1,0]
	v_pk_fma_f32 v[236:237], v[54:55], v[198:199], 0 op_sel_hi:[1,1,0]
	v_pk_fma_f32 v[234:235], v[114:115], v[230:231], v[234:235]
	v_pk_fma_f32 v[236:237], v[56:57], v[232:233], v[236:237]
	v_cvt_scalef32_pk_f32_fp4 v[196:197], v31, 1.0
	v_cvt_scalef32_pk_f32_fp4 v[198:199], v31, 1.0 op_sel:[1,0,0]
	v_cvt_scalef32_pk_f32_fp4 v[230:231], v31, 1.0 op_sel:[0,1,0]
	v_cvt_scalef32_pk_f32_fp4 v[232:233], v31, 1.0 op_sel:[1,1,0]
	v_pk_fma_f32 v[234:235], v[116:117], v[196:197], v[234:235]
	v_pk_fma_f32 v[236:237], v[50:51], v[198:199], v[236:237]
	v_pk_fma_f32 v[234:235], v[118:119], v[230:231], v[234:235]
	v_pk_fma_f32 v[236:237], v[52:53], v[232:233], v[236:237]
	v_cvt_scalef32_pk_f32_fp4 v[196:197], v32, 1.0
	v_cvt_scalef32_pk_f32_fp4 v[198:199], v32, 1.0 op_sel:[1,0,0]
	v_cvt_scalef32_pk_f32_fp4 v[230:231], v32, 1.0 op_sel:[0,1,0]
	v_cvt_scalef32_pk_f32_fp4 v[232:233], v32, 1.0 op_sel:[1,1,0]
	v_pk_fma_f32 v[234:235], v[120:121], v[196:197], v[234:235]
	v_pk_fma_f32 v[236:237], v[46:47], v[198:199], v[236:237]
	v_pk_fma_f32 v[234:235], v[122:123], v[230:231], v[234:235]
	v_pk_fma_f32 v[236:237], v[48:49], v[232:233], v[236:237]
	v_cvt_scalef32_pk_f32_fp4 v[196:197], v33, 1.0
	v_cvt_scalef32_pk_f32_fp4 v[198:199], v33, 1.0 op_sel:[1,0,0]
	v_cvt_scalef32_pk_f32_fp4 v[230:231], v33, 1.0 op_sel:[0,1,0]
	v_cvt_scalef32_pk_f32_fp4 v[232:233], v33, 1.0 op_sel:[1,1,0]
	v_pk_fma_f32 v[234:235], v[126:127], v[196:197], v[234:235]
	v_pk_fma_f32 v[236:237], v[38:39], v[198:199], v[236:237]
	v_pk_fma_f32 v[234:235], v[128:129], v[230:231], v[234:235]
	v_pk_fma_f32 v[236:237], v[40:41], v[232:233], v[236:237]
	s_waitcnt vmcnt(6)
	v_cvt_scalef32_pk_f32_fp4 v[196:197], v26, 1.0
	v_cvt_scalef32_pk_f32_fp4 v[198:199], v26, 1.0 op_sel:[1,0,0]
	v_cvt_scalef32_pk_f32_fp4 v[230:231], v26, 1.0 op_sel:[0,1,0]
	v_cvt_scalef32_pk_f32_fp4 v[232:233], v26, 1.0 op_sel:[1,1,0]
	v_pk_fma_f32 v[234:235], v[130:131], v[196:197], v[234:235]
	v_pk_fma_f32 v[236:237], v[42:43], v[198:199], v[236:237]
	v_pk_fma_f32 v[234:235], v[132:133], v[230:231], v[234:235]
	v_pk_fma_f32 v[236:237], v[44:45], v[232:233], v[236:237]
	v_cvt_scalef32_pk_f32_fp4 v[196:197], v27, 1.0
	v_cvt_scalef32_pk_f32_fp4 v[198:199], v27, 1.0 op_sel:[1,0,0]
	v_cvt_scalef32_pk_f32_fp4 v[230:231], v27, 1.0 op_sel:[0,1,0]
	v_cvt_scalef32_pk_f32_fp4 v[232:233], v27, 1.0 op_sel:[1,1,0]
	v_pk_fma_f32 v[234:235], v[134:135], v[196:197], v[234:235]
	v_pk_fma_f32 v[236:237], v[34:35], v[198:199], v[236:237]
	v_pk_fma_f32 v[234:235], v[136:137], v[230:231], v[234:235]
	v_pk_fma_f32 v[236:237], v[36:37], v[232:233], v[236:237]
	v_cvt_scalef32_pk_f32_fp4 v[196:197], v28, 1.0
	v_cvt_scalef32_pk_f32_fp4 v[198:199], v28, 1.0 op_sel:[1,0,0]
	v_cvt_scalef32_pk_f32_fp4 v[230:231], v28, 1.0 op_sel:[0,1,0]
	v_cvt_scalef32_pk_f32_fp4 v[232:233], v28, 1.0 op_sel:[1,1,0]
	v_pk_fma_f32 v[234:235], v[138:139], v[196:197], v[234:235]
	v_pk_fma_f32 v[236:237], v[140:141], v[198:199], v[236:237]
	v_pk_fma_f32 v[234:235], v[142:143], v[230:231], v[234:235]
	v_pk_fma_f32 v[236:237], v[144:145], v[232:233], v[236:237]
	v_cvt_scalef32_pk_f32_fp4 v[196:197], v29, 1.0
	v_cvt_scalef32_pk_f32_fp4 v[198:199], v29, 1.0 op_sel:[1,0,0]
	v_cvt_scalef32_pk_f32_fp4 v[230:231], v29, 1.0 op_sel:[0,1,0]
	v_cvt_scalef32_pk_f32_fp4 v[232:233], v29, 1.0 op_sel:[1,1,0]
	v_pk_fma_f32 v[234:235], v[146:147], v[196:197], v[234:235]
	v_pk_fma_f32 v[236:237], v[148:149], v[198:199], v[236:237]
	v_pk_fma_f32 v[234:235], v[150:151], v[230:231], v[234:235]
	v_pk_fma_f32 v[236:237], v[152:153], v[232:233], v[236:237]
	v_add_f32_e32 v239, v236, v237
	v_add_f32_e32 v242, v234, v235
	v_add_f32_e32 v239, v242, v239
	s_waitcnt lgkmcnt(0)
	s_nop 0
	v_add_f32_dpp v239, v239, v239 quad_perm:[1,0,3,2] row_mask:0xf bank_mask:0xf bound_ctrl:1
	ds_read_b32 v241, v227 offset:128
	s_waitcnt vmcnt(5)
	v_add_f32_dpp v239, v239, v239 quad_perm:[2,3,0,1] row_mask:0xf bank_mask:0xf bound_ctrl:1
	v_mad_u64_u32 v[242:243], s[6:7], v240, s0, v[84:85]
	global_load_dwordx4 v[30:33], v[242:243], off
	v_add_f32_dpp v239, v239, v239 row_half_mirror row_mask:0xf bank_mask:0xf bound_ctrl:1
	global_load_dwordx4 v[26:29], v[242:243], off offset:256
	s_nop 0
	v_add_f32_dpp v239, v239, v239 row_mirror row_mask:0xf bank_mask:0xf bound_ctrl:1
	ds_write_b32 v244, v239 offset:48
	v_cvt_scalef32_pk_f32_fp4 v[196:197], v66, 1.0
	v_cvt_scalef32_pk_f32_fp4 v[198:199], v66, 1.0 op_sel:[1,0,0]
	v_cvt_scalef32_pk_f32_fp4 v[230:231], v66, 1.0 op_sel:[0,1,0]
	v_cvt_scalef32_pk_f32_fp4 v[232:233], v66, 1.0 op_sel:[1,1,0]
	v_pk_fma_f32 v[234:235], v[112:113], v[196:197], 0 op_sel_hi:[1,1,0]
	v_pk_fma_f32 v[236:237], v[54:55], v[198:199], 0 op_sel_hi:[1,1,0]
	v_pk_fma_f32 v[234:235], v[114:115], v[230:231], v[234:235]
	v_pk_fma_f32 v[236:237], v[56:57], v[232:233], v[236:237]
	v_cvt_scalef32_pk_f32_fp4 v[196:197], v67, 1.0
	v_cvt_scalef32_pk_f32_fp4 v[198:199], v67, 1.0 op_sel:[1,0,0]
	v_cvt_scalef32_pk_f32_fp4 v[230:231], v67, 1.0 op_sel:[0,1,0]
	v_cvt_scalef32_pk_f32_fp4 v[232:233], v67, 1.0 op_sel:[1,1,0]
	v_pk_fma_f32 v[234:235], v[116:117], v[196:197], v[234:235]
	v_pk_fma_f32 v[236:237], v[50:51], v[198:199], v[236:237]
	v_pk_fma_f32 v[234:235], v[118:119], v[230:231], v[234:235]
	v_pk_fma_f32 v[236:237], v[52:53], v[232:233], v[236:237]
	v_cvt_scalef32_pk_f32_fp4 v[196:197], v68, 1.0
	v_cvt_scalef32_pk_f32_fp4 v[198:199], v68, 1.0 op_sel:[1,0,0]
	v_cvt_scalef32_pk_f32_fp4 v[230:231], v68, 1.0 op_sel:[0,1,0]
	v_cvt_scalef32_pk_f32_fp4 v[232:233], v68, 1.0 op_sel:[1,1,0]
	v_pk_fma_f32 v[234:235], v[120:121], v[196:197], v[234:235]
	v_pk_fma_f32 v[236:237], v[46:47], v[198:199], v[236:237]
	v_pk_fma_f32 v[234:235], v[122:123], v[230:231], v[234:235]
	v_pk_fma_f32 v[236:237], v[48:49], v[232:233], v[236:237]
	v_cvt_scalef32_pk_f32_fp4 v[196:197], v69, 1.0
	v_cvt_scalef32_pk_f32_fp4 v[198:199], v69, 1.0 op_sel:[1,0,0]
	v_cvt_scalef32_pk_f32_fp4 v[230:231], v69, 1.0 op_sel:[0,1,0]
	v_cvt_scalef32_pk_f32_fp4 v[232:233], v69, 1.0 op_sel:[1,1,0]
	v_pk_fma_f32 v[234:235], v[126:127], v[196:197], v[234:235]
	v_pk_fma_f32 v[236:237], v[38:39], v[198:199], v[236:237]
	v_pk_fma_f32 v[234:235], v[128:129], v[230:231], v[234:235]
	v_pk_fma_f32 v[236:237], v[40:41], v[232:233], v[236:237]
	s_waitcnt vmcnt(6)
	v_cvt_scalef32_pk_f32_fp4 v[196:197], v58, 1.0
	v_cvt_scalef32_pk_f32_fp4 v[198:199], v58, 1.0 op_sel:[1,0,0]
	v_cvt_scalef32_pk_f32_fp4 v[230:231], v58, 1.0 op_sel:[0,1,0]
	v_cvt_scalef32_pk_f32_fp4 v[232:233], v58, 1.0 op_sel:[1,1,0]
	v_pk_fma_f32 v[234:235], v[130:131], v[196:197], v[234:235]
	v_pk_fma_f32 v[236:237], v[42:43], v[198:199], v[236:237]
	v_pk_fma_f32 v[234:235], v[132:133], v[230:231], v[234:235]
	v_pk_fma_f32 v[236:237], v[44:45], v[232:233], v[236:237]
	v_cvt_scalef32_pk_f32_fp4 v[196:197], v59, 1.0
	v_cvt_scalef32_pk_f32_fp4 v[198:199], v59, 1.0 op_sel:[1,0,0]
	v_cvt_scalef32_pk_f32_fp4 v[230:231], v59, 1.0 op_sel:[0,1,0]
	v_cvt_scalef32_pk_f32_fp4 v[232:233], v59, 1.0 op_sel:[1,1,0]
	v_pk_fma_f32 v[234:235], v[134:135], v[196:197], v[234:235]
	v_pk_fma_f32 v[236:237], v[34:35], v[198:199], v[236:237]
	v_pk_fma_f32 v[234:235], v[136:137], v[230:231], v[234:235]
	v_pk_fma_f32 v[236:237], v[36:37], v[232:233], v[236:237]
	v_cvt_scalef32_pk_f32_fp4 v[196:197], v60, 1.0
	v_cvt_scalef32_pk_f32_fp4 v[198:199], v60, 1.0 op_sel:[1,0,0]
	v_cvt_scalef32_pk_f32_fp4 v[230:231], v60, 1.0 op_sel:[0,1,0]
	v_cvt_scalef32_pk_f32_fp4 v[232:233], v60, 1.0 op_sel:[1,1,0]
	v_pk_fma_f32 v[234:235], v[138:139], v[196:197], v[234:235]
	v_pk_fma_f32 v[236:237], v[140:141], v[198:199], v[236:237]
	v_pk_fma_f32 v[234:235], v[142:143], v[230:231], v[234:235]
	v_pk_fma_f32 v[236:237], v[144:145], v[232:233], v[236:237]
	v_cvt_scalef32_pk_f32_fp4 v[196:197], v61, 1.0
	v_cvt_scalef32_pk_f32_fp4 v[198:199], v61, 1.0 op_sel:[1,0,0]
	v_cvt_scalef32_pk_f32_fp4 v[230:231], v61, 1.0 op_sel:[0,1,0]
	v_cvt_scalef32_pk_f32_fp4 v[232:233], v61, 1.0 op_sel:[1,1,0]
	v_pk_fma_f32 v[234:235], v[146:147], v[196:197], v[234:235]
	v_pk_fma_f32 v[236:237], v[148:149], v[198:199], v[236:237]
	v_pk_fma_f32 v[234:235], v[150:151], v[230:231], v[234:235]
	v_pk_fma_f32 v[236:237], v[152:153], v[232:233], v[236:237]
	v_add_f32_e32 v238, v236, v237
	v_add_f32_e32 v242, v234, v235
	v_add_f32_e32 v238, v242, v238
	s_waitcnt lgkmcnt(0)
	s_nop 0
	v_add_f32_dpp v238, v238, v238 quad_perm:[1,0,3,2] row_mask:0xf bank_mask:0xf bound_ctrl:1
	ds_read_b32 v240, v227 offset:144
	s_waitcnt vmcnt(5)
	v_add_f32_dpp v238, v238, v238 quad_perm:[2,3,0,1] row_mask:0xf bank_mask:0xf bound_ctrl:1
	v_mad_u64_u32 v[242:243], s[6:7], v241, s0, v[84:85]
	global_load_dwordx4 v[66:69], v[242:243], off
	v_add_f32_dpp v238, v238, v238 row_half_mirror row_mask:0xf bank_mask:0xf bound_ctrl:1
	global_load_dwordx4 v[58:61], v[242:243], off offset:256
	s_nop 0
	v_add_f32_dpp v238, v238, v238 row_mirror row_mask:0xf bank_mask:0xf bound_ctrl:1
	ds_write_b32 v244, v238 offset:64
	s_add_i32 s2, s2, 1
	v_add_u32_e32 v227, 64, v227
	v_add_u32_e32 v244, 64, v244
	s_cmp_lt_u32 s2, 6
	s_cbranch_scc1 .Lpu_loop
	v_cvt_scalef32_pk_f32_fp4 v[196:197], v74, 1.0
	v_cvt_scalef32_pk_f32_fp4 v[198:199], v74, 1.0 op_sel:[1,0,0]
	v_cvt_scalef32_pk_f32_fp4 v[230:231], v74, 1.0 op_sel:[0,1,0]
	v_cvt_scalef32_pk_f32_fp4 v[232:233], v74, 1.0 op_sel:[1,1,0]
	v_pk_fma_f32 v[234:235], v[112:113], v[196:197], 0 op_sel_hi:[1,1,0]
	v_pk_fma_f32 v[236:237], v[54:55], v[198:199], 0 op_sel_hi:[1,1,0]
	v_pk_fma_f32 v[234:235], v[114:115], v[230:231], v[234:235]
	v_pk_fma_f32 v[236:237], v[56:57], v[232:233], v[236:237]
	v_cvt_scalef32_pk_f32_fp4 v[196:197], v75, 1.0
	v_cvt_scalef32_pk_f32_fp4 v[198:199], v75, 1.0 op_sel:[1,0,0]
	v_cvt_scalef32_pk_f32_fp4 v[230:231], v75, 1.0 op_sel:[0,1,0]
	v_cvt_scalef32_pk_f32_fp4 v[232:233], v75, 1.0 op_sel:[1,1,0]
	v_pk_fma_f32 v[234:235], v[116:117], v[196:197], v[234:235]
	v_pk_fma_f32 v[236:237], v[50:51], v[198:199], v[236:237]
	v_pk_fma_f32 v[234:235], v[118:119], v[230:231], v[234:235]
	v_pk_fma_f32 v[236:237], v[52:53], v[232:233], v[236:237]
	v_cvt_scalef32_pk_f32_fp4 v[196:197], v76, 1.0
	v_cvt_scalef32_pk_f32_fp4 v[198:199], v76, 1.0 op_sel:[1,0,0]
	v_cvt_scalef32_pk_f32_fp4 v[230:231], v76, 1.0 op_sel:[0,1,0]
	v_cvt_scalef32_pk_f32_fp4 v[232:233], v76, 1.0 op_sel:[1,1,0]
	v_pk_fma_f32 v[234:235], v[120:121], v[196:197], v[234:235]
	v_pk_fma_f32 v[236:237], v[46:47], v[198:199], v[236:237]
	v_pk_fma_f32 v[234:235], v[122:123], v[230:231], v[234:235]
	v_pk_fma_f32 v[236:237], v[48:49], v[232:233], v[236:237]
	v_cvt_scalef32_pk_f32_fp4 v[196:197], v77, 1.0
	v_cvt_scalef32_pk_f32_fp4 v[198:199], v77, 1.0 op_sel:[1,0,0]
	v_cvt_scalef32_pk_f32_fp4 v[230:231], v77, 1.0 op_sel:[0,1,0]
	v_cvt_scalef32_pk_f32_fp4 v[232:233], v77, 1.0 op_sel:[1,1,0]
	v_pk_fma_f32 v[234:235], v[126:127], v[196:197], v[234:235]
	v_pk_fma_f32 v[236:237], v[38:39], v[198:199], v[236:237]
	v_pk_fma_f32 v[234:235], v[128:129], v[230:231], v[234:235]
	v_pk_fma_f32 v[236:237], v[40:41], v[232:233], v[236:237]
	s_waitcnt vmcnt(6)
	v_cvt_scalef32_pk_f32_fp4 v[196:197], v62, 1.0
	v_cvt_scalef32_pk_f32_fp4 v[198:199], v62, 1.0 op_sel:[1,0,0]
	v_cvt_scalef32_pk_f32_fp4 v[230:231], v62, 1.0 op_sel:[0,1,0]
	v_cvt_scalef32_pk_f32_fp4 v[232:233], v62, 1.0 op_sel:[1,1,0]
	v_pk_fma_f32 v[234:235], v[130:131], v[196:197], v[234:235]
	v_pk_fma_f32 v[236:237], v[42:43], v[198:199], v[236:237]
	v_pk_fma_f32 v[234:235], v[132:133], v[230:231], v[234:235]
	v_pk_fma_f32 v[236:237], v[44:45], v[232:233], v[236:237]
	v_cvt_scalef32_pk_f32_fp4 v[196:197], v63, 1.0
	v_cvt_scalef32_pk_f32_fp4 v[198:199], v63, 1.0 op_sel:[1,0,0]
	v_cvt_scalef32_pk_f32_fp4 v[230:231], v63, 1.0 op_sel:[0,1,0]
	v_cvt_scalef32_pk_f32_fp4 v[232:233], v63, 1.0 op_sel:[1,1,0]
	v_pk_fma_f32 v[234:235], v[134:135], v[196:197], v[234:235]
	v_pk_fma_f32 v[236:237], v[34:35], v[198:199], v[236:237]
	v_pk_fma_f32 v[234:235], v[136:137], v[230:231], v[234:235]
	v_pk_fma_f32 v[236:237], v[36:37], v[232:233], v[236:237]
	v_cvt_scalef32_pk_f32_fp4 v[196:197], v64, 1.0
	v_cvt_scalef32_pk_f32_fp4 v[198:199], v64, 1.0 op_sel:[1,0,0]
	v_cvt_scalef32_pk_f32_fp4 v[230:231], v64, 1.0 op_sel:[0,1,0]
	v_cvt_scalef32_pk_f32_fp4 v[232:233], v64, 1.0 op_sel:[1,1,0]
	v_pk_fma_f32 v[234:235], v[138:139], v[196:197], v[234:235]
	v_pk_fma_f32 v[236:237], v[140:141], v[198:199], v[236:237]
	v_pk_fma_f32 v[234:235], v[142:143], v[230:231], v[234:235]
	v_pk_fma_f32 v[236:237], v[144:145], v[232:233], v[236:237]
	v_cvt_scalef32_pk_f32_fp4 v[196:197], v65, 1.0
	v_cvt_scalef32_pk_f32_fp4 v[198:199], v65, 1.0 op_sel:[1,0,0]
	v_cvt_scalef32_pk_f32_fp4 v[230:231], v65, 1.0 op_sel:[0,1,0]
	v_cvt_scalef32_pk_f32_fp4 v[232:233], v65, 1.0 op_sel:[1,1,0]
	v_pk_fma_f32 v[234:235], v[146:147], v[196:197], v[234:235]
	v_pk_fma_f32 v[236:237], v[148:149], v[198:199], v[236:237]
	v_pk_fma_f32 v[234:235], v[150:151], v[230:231], v[234:235]
	v_pk_fma_f32 v[236:237], v[152:153], v[232:233], v[236:237]
	v_add_f32_e32 v239, v236, v237
	v_add_f32_e32 v242, v234, v235
	v_add_f32_e32 v239, v242, v239
	s_waitcnt lgkmcnt(0)
	s_nop 0
	v_add_f32_dpp v239, v239, v239 quad_perm:[1,0,3,2] row_mask:0xf bank_mask:0xf bound_ctrl:1
	ds_read_b32 v241, v227 offset:96
	s_waitcnt vmcnt(5)
	v_add_f32_dpp v239, v239, v239 quad_perm:[2,3,0,1] row_mask:0xf bank_mask:0xf bound_ctrl:1
	v_mad_u64_u32 v[242:243], s[6:7], v240, s0, v[84:85]
	global_load_dwordx4 v[74:77], v[242:243], off
	v_add_f32_dpp v239, v239, v239 row_half_mirror row_mask:0xf bank_mask:0xf bound_ctrl:1
	global_load_dwordx4 v[62:65], v[242:243], off offset:256
	s_nop 0
	v_add_f32_dpp v239, v239, v239 row_mirror row_mask:0xf bank_mask:0xf bound_ctrl:1
	ds_write_b32 v244, v239 offset:16
	v_cvt_scalef32_pk_f32_fp4 v[196:197], v78, 1.0
	v_cvt_scalef32_pk_f32_fp4 v[198:199], v78, 1.0 op_sel:[1,0,0]
	v_cvt_scalef32_pk_f32_fp4 v[230:231], v78, 1.0 op_sel:[0,1,0]
	v_cvt_scalef32_pk_f32_fp4 v[232:233], v78, 1.0 op_sel:[1,1,0]
	v_pk_fma_f32 v[234:235], v[112:113], v[196:197], 0 op_sel_hi:[1,1,0]
	v_pk_fma_f32 v[236:237], v[54:55], v[198:199], 0 op_sel_hi:[1,1,0]
	v_pk_fma_f32 v[234:235], v[114:115], v[230:231], v[234:235]
	v_pk_fma_f32 v[236:237], v[56:57], v[232:233], v[236:237]
	v_cvt_scalef32_pk_f32_fp4 v[196:197], v79, 1.0
	v_cvt_scalef32_pk_f32_fp4 v[198:199], v79, 1.0 op_sel:[1,0,0]
	v_cvt_scalef32_pk_f32_fp4 v[230:231], v79, 1.0 op_sel:[0,1,0]
	v_cvt_scalef32_pk_f32_fp4 v[232:233], v79, 1.0 op_sel:[1,1,0]
	v_pk_fma_f32 v[234:235], v[116:117], v[196:197], v[234:235]
	v_pk_fma_f32 v[236:237], v[50:51], v[198:199], v[236:237]
	v_pk_fma_f32 v[234:235], v[118:119], v[230:231], v[234:235]
	v_pk_fma_f32 v[236:237], v[52:53], v[232:233], v[236:237]
	v_cvt_scalef32_pk_f32_fp4 v[196:197], v80, 1.0
	v_cvt_scalef32_pk_f32_fp4 v[198:199], v80, 1.0 op_sel:[1,0,0]
	v_cvt_scalef32_pk_f32_fp4 v[230:231], v80, 1.0 op_sel:[0,1,0]
	v_cvt_scalef32_pk_f32_fp4 v[232:233], v80, 1.0 op_sel:[1,1,0]
	v_pk_fma_f32 v[234:235], v[120:121], v[196:197], v[234:235]
	v_pk_fma_f32 v[236:237], v[46:47], v[198:199], v[236:237]
	v_pk_fma_f32 v[234:235], v[122:123], v[230:231], v[234:235]
	v_pk_fma_f32 v[236:237], v[48:49], v[232:233], v[236:237]
	v_cvt_scalef32_pk_f32_fp4 v[196:197], v81, 1.0
	v_cvt_scalef32_pk_f32_fp4 v[198:199], v81, 1.0 op_sel:[1,0,0]
	v_cvt_scalef32_pk_f32_fp4 v[230:231], v81, 1.0 op_sel:[0,1,0]
	v_cvt_scalef32_pk_f32_fp4 v[232:233], v81, 1.0 op_sel:[1,1,0]
	v_pk_fma_f32 v[234:235], v[126:127], v[196:197], v[234:235]
	v_pk_fma_f32 v[236:237], v[38:39], v[198:199], v[236:237]
	v_pk_fma_f32 v[234:235], v[128:129], v[230:231], v[234:235]
	v_pk_fma_f32 v[236:237], v[40:41], v[232:233], v[236:237]
	s_waitcnt vmcnt(6)
	v_cvt_scalef32_pk_f32_fp4 v[196:197], v70, 1.0
	v_cvt_scalef32_pk_f32_fp4 v[198:199], v70, 1.0 op_sel:[1,0,0]
	v_cvt_scalef32_pk_f32_fp4 v[230:231], v70, 1.0 op_sel:[0,1,0]
	v_cvt_scalef32_pk_f32_fp4 v[232:233], v70, 1.0 op_sel:[1,1,0]
	v_pk_fma_f32 v[234:235], v[130:131], v[196:197], v[234:235]
	v_pk_fma_f32 v[236:237], v[42:43], v[198:199], v[236:237]
	v_pk_fma_f32 v[234:235], v[132:133], v[230:231], v[234:235]
	v_pk_fma_f32 v[236:237], v[44:45], v[232:233], v[236:237]
	v_cvt_scalef32_pk_f32_fp4 v[196:197], v71, 1.0
	v_cvt_scalef32_pk_f32_fp4 v[198:199], v71, 1.0 op_sel:[1,0,0]
	v_cvt_scalef32_pk_f32_fp4 v[230:231], v71, 1.0 op_sel:[0,1,0]
	v_cvt_scalef32_pk_f32_fp4 v[232:233], v71, 1.0 op_sel:[1,1,0]
	v_pk_fma_f32 v[234:235], v[134:135], v[196:197], v[234:235]
	v_pk_fma_f32 v[236:237], v[34:35], v[198:199], v[236:237]
	v_pk_fma_f32 v[234:235], v[136:137], v[230:231], v[234:235]
	v_pk_fma_f32 v[236:237], v[36:37], v[232:233], v[236:237]
	v_cvt_scalef32_pk_f32_fp4 v[196:197], v72, 1.0
	v_cvt_scalef32_pk_f32_fp4 v[198:199], v72, 1.0 op_sel:[1,0,0]
	v_cvt_scalef32_pk_f32_fp4 v[230:231], v72, 1.0 op_sel:[0,1,0]
	v_cvt_scalef32_pk_f32_fp4 v[232:233], v72, 1.0 op_sel:[1,1,0]
	v_pk_fma_f32 v[234:235], v[138:139], v[196:197], v[234:235]
	v_pk_fma_f32 v[236:237], v[140:141], v[198:199], v[236:237]
	v_pk_fma_f32 v[234:235], v[142:143], v[230:231], v[234:235]
	v_pk_fma_f32 v[236:237], v[144:145], v[232:233], v[236:237]
	v_cvt_scalef32_pk_f32_fp4 v[196:197], v73, 1.0
	v_cvt_scalef32_pk_f32_fp4 v[198:199], v73, 1.0 op_sel:[1,0,0]
	v_cvt_scalef32_pk_f32_fp4 v[230:231], v73, 1.0 op_sel:[0,1,0]
	v_cvt_scalef32_pk_f32_fp4 v[232:233], v73, 1.0 op_sel:[1,1,0]
	v_pk_fma_f32 v[234:235], v[146:147], v[196:197], v[234:235]
	v_pk_fma_f32 v[236:237], v[148:149], v[198:199], v[236:237]
	v_pk_fma_f32 v[234:235], v[150:151], v[230:231], v[234:235]
	v_pk_fma_f32 v[236:237], v[152:153], v[232:233], v[236:237]
	v_add_f32_e32 v238, v236, v237
	v_add_f32_e32 v242, v234, v235
	v_add_f32_e32 v238, v242, v238
	s_waitcnt lgkmcnt(0)
	s_nop 0
	v_add_f32_dpp v238, v238, v238 quad_perm:[1,0,3,2] row_mask:0xf bank_mask:0xf bound_ctrl:1
	ds_read_b32 v240, v227 offset:112
	s_waitcnt vmcnt(5)
	v_add_f32_dpp v238, v238, v238 quad_perm:[2,3,0,1] row_mask:0xf bank_mask:0xf bound_ctrl:1
	v_mad_u64_u32 v[242:243], s[6:7], v241, s0, v[84:85]
	global_load_dwordx4 v[78:81], v[242:243], off
	v_add_f32_dpp v238, v238, v238 row_half_mirror row_mask:0xf bank_mask:0xf bound_ctrl:1
	global_load_dwordx4 v[70:73], v[242:243], off offset:256
	s_nop 0
	v_add_f32_dpp v238, v238, v238 row_mirror row_mask:0xf bank_mask:0xf bound_ctrl:1
	ds_write_b32 v244, v238 offset:32
	v_cvt_scalef32_pk_f32_fp4 v[196:197], v30, 1.0
	v_cvt_scalef32_pk_f32_fp4 v[198:199], v30, 1.0 op_sel:[1,0,0]
	v_cvt_scalef32_pk_f32_fp4 v[230:231], v30, 1.0 op_sel:[0,1,0]
	v_cvt_scalef32_pk_f32_fp4 v[232:233], v30, 1.0 op_sel:[1,1,0]
	v_pk_fma_f32 v[234:235], v[112:113], v[196:197], 0 op_sel_hi:[1,1,0]
	v_pk_fma_f32 v[236:237], v[54:55], v[198:199], 0 op_sel_hi:[1,1,0]
	v_pk_fma_f32 v[234:235], v[114:115], v[230:231], v[234:235]
	v_pk_fma_f32 v[236:237], v[56:57], v[232:233], v[236:237]
	v_cvt_scalef32_pk_f32_fp4 v[196:197], v31, 1.0
	v_cvt_scalef32_pk_f32_fp4 v[198:199], v31, 1.0 op_sel:[1,0,0]
	v_cvt_scalef32_pk_f32_fp4 v[230:231], v31, 1.0 op_sel:[0,1,0]
	v_cvt_scalef32_pk_f32_fp4 v[232:233], v31, 1.0 op_sel:[1,1,0]
	v_pk_fma_f32 v[234:235], v[116:117], v[196:197], v[234:235]
	v_pk_fma_f32 v[236:237], v[50:51], v[198:199], v[236:237]
	v_pk_fma_f32 v[234:235], v[118:119], v[230:231], v[234:235]
	v_pk_fma_f32 v[236:237], v[52:53], v[232:233], v[236:237]
	v_cvt_scalef32_pk_f32_fp4 v[196:197], v32, 1.0
	v_cvt_scalef32_pk_f32_fp4 v[198:199], v32, 1.0 op_sel:[1,0,0]
	v_cvt_scalef32_pk_f32_fp4 v[230:231], v32, 1.0 op_sel:[0,1,0]
	v_cvt_scalef32_pk_f32_fp4 v[232:233], v32, 1.0 op_sel:[1,1,0]
	v_pk_fma_f32 v[234:235], v[120:121], v[196:197], v[234:235]
	v_pk_fma_f32 v[236:237], v[46:47], v[198:199], v[236:237]
	v_pk_fma_f32 v[234:235], v[122:123], v[230:231], v[234:235]
	v_pk_fma_f32 v[236:237], v[48:49], v[232:233], v[236:237]
	v_cvt_scalef32_pk_f32_fp4 v[196:197], v33, 1.0
	v_cvt_scalef32_pk_f32_fp4 v[198:199], v33, 1.0 op_sel:[1,0,0]
	v_cvt_scalef32_pk_f32_fp4 v[230:231], v33, 1.0 op_sel:[0,1,0]
	v_cvt_scalef32_pk_f32_fp4 v[232:233], v33, 1.0 op_sel:[1,1,0]
	v_pk_fma_f32 v[234:235], v[126:127], v[196:197], v[234:235]
	v_pk_fma_f32 v[236:237], v[38:39], v[198:199], v[236:237]
	v_pk_fma_f32 v[234:235], v[128:129], v[230:231], v[234:235]
	v_pk_fma_f32 v[236:237], v[40:41], v[232:233], v[236:237]
	s_waitcnt vmcnt(6)
	v_cvt_scalef32_pk_f32_fp4 v[196:197], v26, 1.0
	v_cvt_scalef32_pk_f32_fp4 v[198:199], v26, 1.0 op_sel:[1,0,0]
	v_cvt_scalef32_pk_f32_fp4 v[230:231], v26, 1.0 op_sel:[0,1,0]
	v_cvt_scalef32_pk_f32_fp4 v[232:233], v26, 1.0 op_sel:[1,1,0]
	v_pk_fma_f32 v[234:235], v[130:131], v[196:197], v[234:235]
	v_pk_fma_f32 v[236:237], v[42:43], v[198:199], v[236:237]
	v_pk_fma_f32 v[234:235], v[132:133], v[230:231], v[234:235]
	v_pk_fma_f32 v[236:237], v[44:45], v[232:233], v[236:237]
	v_cvt_scalef32_pk_f32_fp4 v[196:197], v27, 1.0
	v_cvt_scalef32_pk_f32_fp4 v[198:199], v27, 1.0 op_sel:[1,0,0]
	v_cvt_scalef32_pk_f32_fp4 v[230:231], v27, 1.0 op_sel:[0,1,0]
	v_cvt_scalef32_pk_f32_fp4 v[232:233], v27, 1.0 op_sel:[1,1,0]
	v_pk_fma_f32 v[234:235], v[134:135], v[196:197], v[234:235]
	v_pk_fma_f32 v[236:237], v[34:35], v[198:199], v[236:237]
	v_pk_fma_f32 v[234:235], v[136:137], v[230:231], v[234:235]
	v_pk_fma_f32 v[236:237], v[36:37], v[232:233], v[236:237]
	v_cvt_scalef32_pk_f32_fp4 v[196:197], v28, 1.0
	v_cvt_scalef32_pk_f32_fp4 v[198:199], v28, 1.0 op_sel:[1,0,0]
	v_cvt_scalef32_pk_f32_fp4 v[230:231], v28, 1.0 op_sel:[0,1,0]
	v_cvt_scalef32_pk_f32_fp4 v[232:233], v28, 1.0 op_sel:[1,1,0]
	v_pk_fma_f32 v[234:235], v[138:139], v[196:197], v[234:235]
	v_pk_fma_f32 v[236:237], v[140:141], v[198:199], v[236:237]
	v_pk_fma_f32 v[234:235], v[142:143], v[230:231], v[234:235]
	v_pk_fma_f32 v[236:237], v[144:145], v[232:233], v[236:237]
	v_cvt_scalef32_pk_f32_fp4 v[196:197], v29, 1.0
	v_cvt_scalef32_pk_f32_fp4 v[198:199], v29, 1.0 op_sel:[1,0,0]
	v_cvt_scalef32_pk_f32_fp4 v[230:231], v29, 1.0 op_sel:[0,1,0]
	v_cvt_scalef32_pk_f32_fp4 v[232:233], v29, 1.0 op_sel:[1,1,0]
	v_pk_fma_f32 v[234:235], v[146:147], v[196:197], v[234:235]
	v_pk_fma_f32 v[236:237], v[148:149], v[198:199], v[236:237]
	v_pk_fma_f32 v[234:235], v[150:151], v[230:231], v[234:235]
	v_pk_fma_f32 v[236:237], v[152:153], v[232:233], v[236:237]
	v_add_f32_e32 v239, v236, v237
	v_add_f32_e32 v242, v234, v235
	v_add_f32_e32 v239, v242, v239
	s_waitcnt lgkmcnt(0)
	s_nop 0
	v_add_f32_dpp v239, v239, v239 quad_perm:[1,0,3,2] row_mask:0xf bank_mask:0xf bound_ctrl:1
	s_waitcnt vmcnt(5)
	s_nop 0
	v_add_f32_dpp v239, v239, v239 quad_perm:[2,3,0,1] row_mask:0xf bank_mask:0xf bound_ctrl:1
	v_mad_u64_u32 v[242:243], s[6:7], v240, s0, v[84:85]
	global_load_dwordx4 v[30:33], v[242:243], off
	v_add_f32_dpp v239, v239, v239 row_half_mirror row_mask:0xf bank_mask:0xf bound_ctrl:1
	global_load_dwordx4 v[26:29], v[242:243], off offset:256
	s_nop 0
	v_add_f32_dpp v239, v239, v239 row_mirror row_mask:0xf bank_mask:0xf bound_ctrl:1
	ds_write_b32 v244, v239 offset:48
	v_cvt_scalef32_pk_f32_fp4 v[196:197], v66, 1.0
	v_cvt_scalef32_pk_f32_fp4 v[198:199], v66, 1.0 op_sel:[1,0,0]
	v_cvt_scalef32_pk_f32_fp4 v[230:231], v66, 1.0 op_sel:[0,1,0]
	v_cvt_scalef32_pk_f32_fp4 v[232:233], v66, 1.0 op_sel:[1,1,0]
	v_pk_fma_f32 v[234:235], v[112:113], v[196:197], 0 op_sel_hi:[1,1,0]
	v_pk_fma_f32 v[236:237], v[54:55], v[198:199], 0 op_sel_hi:[1,1,0]
	v_pk_fma_f32 v[234:235], v[114:115], v[230:231], v[234:235]
	v_pk_fma_f32 v[236:237], v[56:57], v[232:233], v[236:237]
	v_cvt_scalef32_pk_f32_fp4 v[196:197], v67, 1.0
	v_cvt_scalef32_pk_f32_fp4 v[198:199], v67, 1.0 op_sel:[1,0,0]
	v_cvt_scalef32_pk_f32_fp4 v[230:231], v67, 1.0 op_sel:[0,1,0]
	v_cvt_scalef32_pk_f32_fp4 v[232:233], v67, 1.0 op_sel:[1,1,0]
	v_pk_fma_f32 v[234:235], v[116:117], v[196:197], v[234:235]
	v_pk_fma_f32 v[236:237], v[50:51], v[198:199], v[236:237]
	v_pk_fma_f32 v[234:235], v[118:119], v[230:231], v[234:235]
	v_pk_fma_f32 v[236:237], v[52:53], v[232:233], v[236:237]
	v_cvt_scalef32_pk_f32_fp4 v[196:197], v68, 1.0
	v_cvt_scalef32_pk_f32_fp4 v[198:199], v68, 1.0 op_sel:[1,0,0]
	v_cvt_scalef32_pk_f32_fp4 v[230:231], v68, 1.0 op_sel:[0,1,0]
	v_cvt_scalef32_pk_f32_fp4 v[232:233], v68, 1.0 op_sel:[1,1,0]
	v_pk_fma_f32 v[234:235], v[120:121], v[196:197], v[234:235]
	v_pk_fma_f32 v[236:237], v[46:47], v[198:199], v[236:237]
	v_pk_fma_f32 v[234:235], v[122:123], v[230:231], v[234:235]
	v_pk_fma_f32 v[236:237], v[48:49], v[232:233], v[236:237]
	v_cvt_scalef32_pk_f32_fp4 v[196:197], v69, 1.0
	v_cvt_scalef32_pk_f32_fp4 v[198:199], v69, 1.0 op_sel:[1,0,0]
	v_cvt_scalef32_pk_f32_fp4 v[230:231], v69, 1.0 op_sel:[0,1,0]
	v_cvt_scalef32_pk_f32_fp4 v[232:233], v69, 1.0 op_sel:[1,1,0]
	v_pk_fma_f32 v[234:235], v[126:127], v[196:197], v[234:235]
	v_pk_fma_f32 v[236:237], v[38:39], v[198:199], v[236:237]
	v_pk_fma_f32 v[234:235], v[128:129], v[230:231], v[234:235]
	v_pk_fma_f32 v[236:237], v[40:41], v[232:233], v[236:237]
	s_waitcnt vmcnt(6)
	v_cvt_scalef32_pk_f32_fp4 v[196:197], v58, 1.0
	v_cvt_scalef32_pk_f32_fp4 v[198:199], v58, 1.0 op_sel:[1,0,0]
	v_cvt_scalef32_pk_f32_fp4 v[230:231], v58, 1.0 op_sel:[0,1,0]
	v_cvt_scalef32_pk_f32_fp4 v[232:233], v58, 1.0 op_sel:[1,1,0]
	v_pk_fma_f32 v[234:235], v[130:131], v[196:197], v[234:235]
	v_pk_fma_f32 v[236:237], v[42:43], v[198:199], v[236:237]
	v_pk_fma_f32 v[234:235], v[132:133], v[230:231], v[234:235]
	v_pk_fma_f32 v[236:237], v[44:45], v[232:233], v[236:237]
	v_cvt_scalef32_pk_f32_fp4 v[196:197], v59, 1.0
	v_cvt_scalef32_pk_f32_fp4 v[198:199], v59, 1.0 op_sel:[1,0,0]
	v_cvt_scalef32_pk_f32_fp4 v[230:231], v59, 1.0 op_sel:[0,1,0]
	v_cvt_scalef32_pk_f32_fp4 v[232:233], v59, 1.0 op_sel:[1,1,0]
	v_pk_fma_f32 v[234:235], v[134:135], v[196:197], v[234:235]
	v_pk_fma_f32 v[236:237], v[34:35], v[198:199], v[236:237]
	v_pk_fma_f32 v[234:235], v[136:137], v[230:231], v[234:235]
	v_pk_fma_f32 v[236:237], v[36:37], v[232:233], v[236:237]
	v_cvt_scalef32_pk_f32_fp4 v[196:197], v60, 1.0
	v_cvt_scalef32_pk_f32_fp4 v[198:199], v60, 1.0 op_sel:[1,0,0]
	v_cvt_scalef32_pk_f32_fp4 v[230:231], v60, 1.0 op_sel:[0,1,0]
	v_cvt_scalef32_pk_f32_fp4 v[232:233], v60, 1.0 op_sel:[1,1,0]
	v_pk_fma_f32 v[234:235], v[138:139], v[196:197], v[234:235]
	v_pk_fma_f32 v[236:237], v[140:141], v[198:199], v[236:237]
	v_pk_fma_f32 v[234:235], v[142:143], v[230:231], v[234:235]
	v_pk_fma_f32 v[236:237], v[144:145], v[232:233], v[236:237]
	v_cvt_scalef32_pk_f32_fp4 v[196:197], v61, 1.0
	v_cvt_scalef32_pk_f32_fp4 v[198:199], v61, 1.0 op_sel:[1,0,0]
	v_cvt_scalef32_pk_f32_fp4 v[230:231], v61, 1.0 op_sel:[0,1,0]
	v_cvt_scalef32_pk_f32_fp4 v[232:233], v61, 1.0 op_sel:[1,1,0]
	v_pk_fma_f32 v[234:235], v[146:147], v[196:197], v[234:235]
	v_pk_fma_f32 v[236:237], v[148:149], v[198:199], v[236:237]
	v_pk_fma_f32 v[234:235], v[150:151], v[230:231], v[234:235]
	v_pk_fma_f32 v[236:237], v[152:153], v[232:233], v[236:237]
	v_add_f32_e32 v238, v236, v237
	v_add_f32_e32 v242, v234, v235
	v_add_f32_e32 v238, v242, v238
	s_waitcnt lgkmcnt(0)
	s_nop 0
	v_add_f32_dpp v238, v238, v238 quad_perm:[1,0,3,2] row_mask:0xf bank_mask:0xf bound_ctrl:1
	s_waitcnt vmcnt(5)
	s_nop 0
	v_add_f32_dpp v238, v238, v238 quad_perm:[2,3,0,1] row_mask:0xf bank_mask:0xf bound_ctrl:1
	s_nop 1
	v_add_f32_dpp v238, v238, v238 row_half_mirror row_mask:0xf bank_mask:0xf bound_ctrl:1
	s_nop 1
	v_add_f32_dpp v238, v238, v238 row_mirror row_mask:0xf bank_mask:0xf bound_ctrl:1
	ds_write_b32 v244, v238 offset:64
	v_cvt_scalef32_pk_f32_fp4 v[196:197], v74, 1.0
	v_cvt_scalef32_pk_f32_fp4 v[198:199], v74, 1.0 op_sel:[1,0,0]
	v_cvt_scalef32_pk_f32_fp4 v[230:231], v74, 1.0 op_sel:[0,1,0]
	v_cvt_scalef32_pk_f32_fp4 v[232:233], v74, 1.0 op_sel:[1,1,0]
	v_pk_fma_f32 v[234:235], v[112:113], v[196:197], 0 op_sel_hi:[1,1,0]
	v_pk_fma_f32 v[236:237], v[54:55], v[198:199], 0 op_sel_hi:[1,1,0]
	v_pk_fma_f32 v[234:235], v[114:115], v[230:231], v[234:235]
	v_pk_fma_f32 v[236:237], v[56:57], v[232:233], v[236:237]
	v_cvt_scalef32_pk_f32_fp4 v[196:197], v75, 1.0
	v_cvt_scalef32_pk_f32_fp4 v[198:199], v75, 1.0 op_sel:[1,0,0]
	v_cvt_scalef32_pk_f32_fp4 v[230:231], v75, 1.0 op_sel:[0,1,0]
	v_cvt_scalef32_pk_f32_fp4 v[232:233], v75, 1.0 op_sel:[1,1,0]
	v_pk_fma_f32 v[234:235], v[116:117], v[196:197], v[234:235]
	v_pk_fma_f32 v[236:237], v[50:51], v[198:199], v[236:237]
	v_pk_fma_f32 v[234:235], v[118:119], v[230:231], v[234:235]
	v_pk_fma_f32 v[236:237], v[52:53], v[232:233], v[236:237]
	v_cvt_scalef32_pk_f32_fp4 v[196:197], v76, 1.0
	v_cvt_scalef32_pk_f32_fp4 v[198:199], v76, 1.0 op_sel:[1,0,0]
	v_cvt_scalef32_pk_f32_fp4 v[230:231], v76, 1.0 op_sel:[0,1,0]
	v_cvt_scalef32_pk_f32_fp4 v[232:233], v76, 1.0 op_sel:[1,1,0]
	v_pk_fma_f32 v[234:235], v[120:121], v[196:197], v[234:235]
	v_pk_fma_f32 v[236:237], v[46:47], v[198:199], v[236:237]
	v_pk_fma_f32 v[234:235], v[122:123], v[230:231], v[234:235]
	v_pk_fma_f32 v[236:237], v[48:49], v[232:233], v[236:237]
	v_cvt_scalef32_pk_f32_fp4 v[196:197], v77, 1.0
	v_cvt_scalef32_pk_f32_fp4 v[198:199], v77, 1.0 op_sel:[1,0,0]
	v_cvt_scalef32_pk_f32_fp4 v[230:231], v77, 1.0 op_sel:[0,1,0]
	v_cvt_scalef32_pk_f32_fp4 v[232:233], v77, 1.0 op_sel:[1,1,0]
	v_pk_fma_f32 v[234:235], v[126:127], v[196:197], v[234:235]
	v_pk_fma_f32 v[236:237], v[38:39], v[198:199], v[236:237]
	v_pk_fma_f32 v[234:235], v[128:129], v[230:231], v[234:235]
	v_pk_fma_f32 v[236:237], v[40:41], v[232:233], v[236:237]
	s_waitcnt vmcnt(4)
	v_cvt_scalef32_pk_f32_fp4 v[196:197], v62, 1.0
	v_cvt_scalef32_pk_f32_fp4 v[198:199], v62, 1.0 op_sel:[1,0,0]
	v_cvt_scalef32_pk_f32_fp4 v[230:231], v62, 1.0 op_sel:[0,1,0]
	v_cvt_scalef32_pk_f32_fp4 v[232:233], v62, 1.0 op_sel:[1,1,0]
	v_pk_fma_f32 v[234:235], v[130:131], v[196:197], v[234:235]
	v_pk_fma_f32 v[236:237], v[42:43], v[198:199], v[236:237]
	v_pk_fma_f32 v[234:235], v[132:133], v[230:231], v[234:235]
	v_pk_fma_f32 v[236:237], v[44:45], v[232:233], v[236:237]
	v_cvt_scalef32_pk_f32_fp4 v[196:197], v63, 1.0
	v_cvt_scalef32_pk_f32_fp4 v[198:199], v63, 1.0 op_sel:[1,0,0]
	v_cvt_scalef32_pk_f32_fp4 v[230:231], v63, 1.0 op_sel:[0,1,0]
	v_cvt_scalef32_pk_f32_fp4 v[232:233], v63, 1.0 op_sel:[1,1,0]
	v_pk_fma_f32 v[234:235], v[134:135], v[196:197], v[234:235]
	v_pk_fma_f32 v[236:237], v[34:35], v[198:199], v[236:237]
	v_pk_fma_f32 v[234:235], v[136:137], v[230:231], v[234:235]
	v_pk_fma_f32 v[236:237], v[36:37], v[232:233], v[236:237]
	v_cvt_scalef32_pk_f32_fp4 v[196:197], v64, 1.0
	v_cvt_scalef32_pk_f32_fp4 v[198:199], v64, 1.0 op_sel:[1,0,0]
	v_cvt_scalef32_pk_f32_fp4 v[230:231], v64, 1.0 op_sel:[0,1,0]
	v_cvt_scalef32_pk_f32_fp4 v[232:233], v64, 1.0 op_sel:[1,1,0]
	v_pk_fma_f32 v[234:235], v[138:139], v[196:197], v[234:235]
	v_pk_fma_f32 v[236:237], v[140:141], v[198:199], v[236:237]
	v_pk_fma_f32 v[234:235], v[142:143], v[230:231], v[234:235]
	v_pk_fma_f32 v[236:237], v[144:145], v[232:233], v[236:237]
	v_cvt_scalef32_pk_f32_fp4 v[196:197], v65, 1.0
	v_cvt_scalef32_pk_f32_fp4 v[198:199], v65, 1.0 op_sel:[1,0,0]
	v_cvt_scalef32_pk_f32_fp4 v[230:231], v65, 1.0 op_sel:[0,1,0]
	v_cvt_scalef32_pk_f32_fp4 v[232:233], v65, 1.0 op_sel:[1,1,0]
	v_pk_fma_f32 v[234:235], v[146:147], v[196:197], v[234:235]
	v_pk_fma_f32 v[236:237], v[148:149], v[198:199], v[236:237]
	v_pk_fma_f32 v[234:235], v[150:151], v[230:231], v[234:235]
	v_pk_fma_f32 v[236:237], v[152:153], v[232:233], v[236:237]
	v_add_f32_e32 v239, v236, v237
	v_add_f32_e32 v242, v234, v235
	v_add_f32_e32 v239, v242, v239
	s_waitcnt lgkmcnt(0)
	s_nop 0
	v_add_f32_dpp v239, v239, v239 quad_perm:[1,0,3,2] row_mask:0xf bank_mask:0xf bound_ctrl:1
	s_waitcnt vmcnt(3)
	s_nop 0
	v_add_f32_dpp v239, v239, v239 quad_perm:[2,3,0,1] row_mask:0xf bank_mask:0xf bound_ctrl:1
	s_nop 1
	v_add_f32_dpp v239, v239, v239 row_half_mirror row_mask:0xf bank_mask:0xf bound_ctrl:1
	s_nop 1
	v_add_f32_dpp v239, v239, v239 row_mirror row_mask:0xf bank_mask:0xf bound_ctrl:1
	ds_write_b32 v244, v239 offset:80
	v_cvt_scalef32_pk_f32_fp4 v[196:197], v78, 1.0
	v_cvt_scalef32_pk_f32_fp4 v[198:199], v78, 1.0 op_sel:[1,0,0]
	v_cvt_scalef32_pk_f32_fp4 v[230:231], v78, 1.0 op_sel:[0,1,0]
	v_cvt_scalef32_pk_f32_fp4 v[232:233], v78, 1.0 op_sel:[1,1,0]
	v_pk_fma_f32 v[234:235], v[112:113], v[196:197], 0 op_sel_hi:[1,1,0]
	v_pk_fma_f32 v[236:237], v[54:55], v[198:199], 0 op_sel_hi:[1,1,0]
	v_pk_fma_f32 v[234:235], v[114:115], v[230:231], v[234:235]
	v_pk_fma_f32 v[236:237], v[56:57], v[232:233], v[236:237]
	v_cvt_scalef32_pk_f32_fp4 v[196:197], v79, 1.0
	v_cvt_scalef32_pk_f32_fp4 v[198:199], v79, 1.0 op_sel:[1,0,0]
	v_cvt_scalef32_pk_f32_fp4 v[230:231], v79, 1.0 op_sel:[0,1,0]
	v_cvt_scalef32_pk_f32_fp4 v[232:233], v79, 1.0 op_sel:[1,1,0]
	v_pk_fma_f32 v[234:235], v[116:117], v[196:197], v[234:235]
	v_pk_fma_f32 v[236:237], v[50:51], v[198:199], v[236:237]
	v_pk_fma_f32 v[234:235], v[118:119], v[230:231], v[234:235]
	v_pk_fma_f32 v[236:237], v[52:53], v[232:233], v[236:237]
	v_cvt_scalef32_pk_f32_fp4 v[196:197], v80, 1.0
	v_cvt_scalef32_pk_f32_fp4 v[198:199], v80, 1.0 op_sel:[1,0,0]
	v_cvt_scalef32_pk_f32_fp4 v[230:231], v80, 1.0 op_sel:[0,1,0]
	v_cvt_scalef32_pk_f32_fp4 v[232:233], v80, 1.0 op_sel:[1,1,0]
	v_pk_fma_f32 v[234:235], v[120:121], v[196:197], v[234:235]
	v_pk_fma_f32 v[236:237], v[46:47], v[198:199], v[236:237]
	v_pk_fma_f32 v[234:235], v[122:123], v[230:231], v[234:235]
	v_pk_fma_f32 v[236:237], v[48:49], v[232:233], v[236:237]
	v_cvt_scalef32_pk_f32_fp4 v[196:197], v81, 1.0
	v_cvt_scalef32_pk_f32_fp4 v[198:199], v81, 1.0 op_sel:[1,0,0]
	v_cvt_scalef32_pk_f32_fp4 v[230:231], v81, 1.0 op_sel:[0,1,0]
	v_cvt_scalef32_pk_f32_fp4 v[232:233], v81, 1.0 op_sel:[1,1,0]
	v_pk_fma_f32 v[234:235], v[126:127], v[196:197], v[234:235]
	v_pk_fma_f32 v[236:237], v[38:39], v[198:199], v[236:237]
	v_pk_fma_f32 v[234:235], v[128:129], v[230:231], v[234:235]
	v_pk_fma_f32 v[236:237], v[40:41], v[232:233], v[236:237]
	s_waitcnt vmcnt(2)
	v_cvt_scalef32_pk_f32_fp4 v[196:197], v70, 1.0
	v_cvt_scalef32_pk_f32_fp4 v[198:199], v70, 1.0 op_sel:[1,0,0]
	v_cvt_scalef32_pk_f32_fp4 v[230:231], v70, 1.0 op_sel:[0,1,0]
	v_cvt_scalef32_pk_f32_fp4 v[232:233], v70, 1.0 op_sel:[1,1,0]
	v_pk_fma_f32 v[234:235], v[130:131], v[196:197], v[234:235]
	v_pk_fma_f32 v[236:237], v[42:43], v[198:199], v[236:237]
	v_pk_fma_f32 v[234:235], v[132:133], v[230:231], v[234:235]
	v_pk_fma_f32 v[236:237], v[44:45], v[232:233], v[236:237]
	v_cvt_scalef32_pk_f32_fp4 v[196:197], v71, 1.0
	v_cvt_scalef32_pk_f32_fp4 v[198:199], v71, 1.0 op_sel:[1,0,0]
	v_cvt_scalef32_pk_f32_fp4 v[230:231], v71, 1.0 op_sel:[0,1,0]
	v_cvt_scalef32_pk_f32_fp4 v[232:233], v71, 1.0 op_sel:[1,1,0]
	v_pk_fma_f32 v[234:235], v[134:135], v[196:197], v[234:235]
	v_pk_fma_f32 v[236:237], v[34:35], v[198:199], v[236:237]
	v_pk_fma_f32 v[234:235], v[136:137], v[230:231], v[234:235]
	v_pk_fma_f32 v[236:237], v[36:37], v[232:233], v[236:237]
	v_cvt_scalef32_pk_f32_fp4 v[196:197], v72, 1.0
	v_cvt_scalef32_pk_f32_fp4 v[198:199], v72, 1.0 op_sel:[1,0,0]
	v_cvt_scalef32_pk_f32_fp4 v[230:231], v72, 1.0 op_sel:[0,1,0]
	v_cvt_scalef32_pk_f32_fp4 v[232:233], v72, 1.0 op_sel:[1,1,0]
	v_pk_fma_f32 v[234:235], v[138:139], v[196:197], v[234:235]
	v_pk_fma_f32 v[236:237], v[140:141], v[198:199], v[236:237]
	v_pk_fma_f32 v[234:235], v[142:143], v[230:231], v[234:235]
	v_pk_fma_f32 v[236:237], v[144:145], v[232:233], v[236:237]
	v_cvt_scalef32_pk_f32_fp4 v[196:197], v73, 1.0
	v_cvt_scalef32_pk_f32_fp4 v[198:199], v73, 1.0 op_sel:[1,0,0]
	v_cvt_scalef32_pk_f32_fp4 v[230:231], v73, 1.0 op_sel:[0,1,0]
	v_cvt_scalef32_pk_f32_fp4 v[232:233], v73, 1.0 op_sel:[1,1,0]
	v_pk_fma_f32 v[234:235], v[146:147], v[196:197], v[234:235]
	v_pk_fma_f32 v[236:237], v[148:149], v[198:199], v[236:237]
	v_pk_fma_f32 v[234:235], v[150:151], v[230:231], v[234:235]
	v_pk_fma_f32 v[236:237], v[152:153], v[232:233], v[236:237]
	v_add_f32_e32 v238, v236, v237
	v_add_f32_e32 v242, v234, v235
	v_add_f32_e32 v238, v242, v238
	s_waitcnt lgkmcnt(0)
	s_nop 0
	v_add_f32_dpp v238, v238, v238 quad_perm:[1,0,3,2] row_mask:0xf bank_mask:0xf bound_ctrl:1
	s_waitcnt vmcnt(1)
	s_nop 0
	v_add_f32_dpp v238, v238, v238 quad_perm:[2,3,0,1] row_mask:0xf bank_mask:0xf bound_ctrl:1
	s_nop 1
	v_add_f32_dpp v238, v238, v238 row_half_mirror row_mask:0xf bank_mask:0xf bound_ctrl:1
	s_nop 1
	v_add_f32_dpp v238, v238, v238 row_mirror row_mask:0xf bank_mask:0xf bound_ctrl:1
	ds_write_b32 v244, v238 offset:96
	v_cvt_scalef32_pk_f32_fp4 v[196:197], v30, 1.0
	v_cvt_scalef32_pk_f32_fp4 v[198:199], v30, 1.0 op_sel:[1,0,0]
	v_cvt_scalef32_pk_f32_fp4 v[230:231], v30, 1.0 op_sel:[0,1,0]
	v_cvt_scalef32_pk_f32_fp4 v[232:233], v30, 1.0 op_sel:[1,1,0]
	v_pk_fma_f32 v[234:235], v[112:113], v[196:197], 0 op_sel_hi:[1,1,0]
	v_pk_fma_f32 v[236:237], v[54:55], v[198:199], 0 op_sel_hi:[1,1,0]
	v_pk_fma_f32 v[234:235], v[114:115], v[230:231], v[234:235]
	v_pk_fma_f32 v[236:237], v[56:57], v[232:233], v[236:237]
	v_cvt_scalef32_pk_f32_fp4 v[196:197], v31, 1.0
	v_cvt_scalef32_pk_f32_fp4 v[198:199], v31, 1.0 op_sel:[1,0,0]
	v_cvt_scalef32_pk_f32_fp4 v[230:231], v31, 1.0 op_sel:[0,1,0]
	v_cvt_scalef32_pk_f32_fp4 v[232:233], v31, 1.0 op_sel:[1,1,0]
	v_pk_fma_f32 v[234:235], v[116:117], v[196:197], v[234:235]
	v_pk_fma_f32 v[236:237], v[50:51], v[198:199], v[236:237]
	v_pk_fma_f32 v[234:235], v[118:119], v[230:231], v[234:235]
	v_pk_fma_f32 v[236:237], v[52:53], v[232:233], v[236:237]
	v_cvt_scalef32_pk_f32_fp4 v[196:197], v32, 1.0
	v_cvt_scalef32_pk_f32_fp4 v[198:199], v32, 1.0 op_sel:[1,0,0]
	v_cvt_scalef32_pk_f32_fp4 v[230:231], v32, 1.0 op_sel:[0,1,0]
	v_cvt_scalef32_pk_f32_fp4 v[232:233], v32, 1.0 op_sel:[1,1,0]
	v_pk_fma_f32 v[234:235], v[120:121], v[196:197], v[234:235]
	v_pk_fma_f32 v[236:237], v[46:47], v[198:199], v[236:237]
	v_pk_fma_f32 v[234:235], v[122:123], v[230:231], v[234:235]
	v_pk_fma_f32 v[236:237], v[48:49], v[232:233], v[236:237]
	v_cvt_scalef32_pk_f32_fp4 v[196:197], v33, 1.0
	v_cvt_scalef32_pk_f32_fp4 v[198:199], v33, 1.0 op_sel:[1,0,0]
	v_cvt_scalef32_pk_f32_fp4 v[230:231], v33, 1.0 op_sel:[0,1,0]
	v_cvt_scalef32_pk_f32_fp4 v[232:233], v33, 1.0 op_sel:[1,1,0]
	v_pk_fma_f32 v[234:235], v[126:127], v[196:197], v[234:235]
	v_pk_fma_f32 v[236:237], v[38:39], v[198:199], v[236:237]
	v_pk_fma_f32 v[234:235], v[128:129], v[230:231], v[234:235]
	v_pk_fma_f32 v[236:237], v[40:41], v[232:233], v[236:237]
	s_waitcnt vmcnt(0)
	v_cvt_scalef32_pk_f32_fp4 v[196:197], v26, 1.0
	v_cvt_scalef32_pk_f32_fp4 v[198:199], v26, 1.0 op_sel:[1,0,0]
	v_cvt_scalef32_pk_f32_fp4 v[230:231], v26, 1.0 op_sel:[0,1,0]
	v_cvt_scalef32_pk_f32_fp4 v[232:233], v26, 1.0 op_sel:[1,1,0]
	v_pk_fma_f32 v[234:235], v[130:131], v[196:197], v[234:235]
	v_pk_fma_f32 v[236:237], v[42:43], v[198:199], v[236:237]
	v_pk_fma_f32 v[234:235], v[132:133], v[230:231], v[234:235]
	v_pk_fma_f32 v[236:237], v[44:45], v[232:233], v[236:237]
	v_cvt_scalef32_pk_f32_fp4 v[196:197], v27, 1.0
	v_cvt_scalef32_pk_f32_fp4 v[198:199], v27, 1.0 op_sel:[1,0,0]
	v_cvt_scalef32_pk_f32_fp4 v[230:231], v27, 1.0 op_sel:[0,1,0]
	v_cvt_scalef32_pk_f32_fp4 v[232:233], v27, 1.0 op_sel:[1,1,0]
	v_pk_fma_f32 v[234:235], v[134:135], v[196:197], v[234:235]
	v_pk_fma_f32 v[236:237], v[34:35], v[198:199], v[236:237]
	v_pk_fma_f32 v[234:235], v[136:137], v[230:231], v[234:235]
	v_pk_fma_f32 v[236:237], v[36:37], v[232:233], v[236:237]
	v_cvt_scalef32_pk_f32_fp4 v[196:197], v28, 1.0
	v_cvt_scalef32_pk_f32_fp4 v[198:199], v28, 1.0 op_sel:[1,0,0]
	v_cvt_scalef32_pk_f32_fp4 v[230:231], v28, 1.0 op_sel:[0,1,0]
	v_cvt_scalef32_pk_f32_fp4 v[232:233], v28, 1.0 op_sel:[1,1,0]
	v_pk_fma_f32 v[234:235], v[138:139], v[196:197], v[234:235]
	v_pk_fma_f32 v[236:237], v[140:141], v[198:199], v[236:237]
	v_pk_fma_f32 v[234:235], v[142:143], v[230:231], v[234:235]
	v_pk_fma_f32 v[236:237], v[144:145], v[232:233], v[236:237]
	v_cvt_scalef32_pk_f32_fp4 v[196:197], v29, 1.0
	v_cvt_scalef32_pk_f32_fp4 v[198:199], v29, 1.0 op_sel:[1,0,0]
	v_cvt_scalef32_pk_f32_fp4 v[230:231], v29, 1.0 op_sel:[0,1,0]
	v_cvt_scalef32_pk_f32_fp4 v[232:233], v29, 1.0 op_sel:[1,1,0]
	v_pk_fma_f32 v[234:235], v[146:147], v[196:197], v[234:235]
	v_pk_fma_f32 v[236:237], v[148:149], v[198:199], v[236:237]
	v_pk_fma_f32 v[234:235], v[150:151], v[230:231], v[234:235]
	v_pk_fma_f32 v[236:237], v[152:153], v[232:233], v[236:237]
	v_add_f32_e32 v239, v236, v237
	v_add_f32_e32 v242, v234, v235
	v_add_f32_e32 v239, v242, v239
	s_waitcnt lgkmcnt(0)
	s_nop 0
	v_add_f32_dpp v239, v239, v239 quad_perm:[1,0,3,2] row_mask:0xf bank_mask:0xf bound_ctrl:1
	s_nop 1
	v_add_f32_dpp v239, v239, v239 quad_perm:[2,3,0,1] row_mask:0xf bank_mask:0xf bound_ctrl:1
	s_nop 1
	v_add_f32_dpp v239, v239, v239 row_half_mirror row_mask:0xf bank_mask:0xf bound_ctrl:1
	s_nop 1
	v_add_f32_dpp v239, v239, v239 row_mirror row_mask:0xf bank_mask:0xf bound_ctrl:1
	ds_write_b32 v244, v239 offset:112
